# v44 + norm_rows: DPP wave_sum and hoisted gamma/scale/shift loads (issued with the x loads)
# speedup vs baseline: 1.0094x; 1.0001x over previous
; __device__ __forceinline__ u32x2 pk4(f32x4 v) { u32x2 r; r.x = pk2(v[0], v[1]); r.y = pk2(v[2], v[3]); return r; }
; __device__ __forceinline__ float dot4(f32x4 v) { return (v[0] * v[0] + v[1] * v[1]) + (v[2] * v[2] + v[3] * v[3]); }
; __device__ __forceinline__ int fresh_tid() { int t = threadIdx.x; asm volatile("" : "+v"(t)); return t; }
; __device__ __forceinline__ void norm_row_compute(const float* xp, const float* g, const float* mp, int shoff, int scoff, int lane, u32x2 (&outv)[4], const float* pp = nullptr, float* wb = nullptr) {
;     f32x4 v[4]; float ss = 0.f;
; #pragma unroll
;     for (int j = 0; j < 4; ++j) { v[j] = *(const f32x4*)(xp + j * 256 + lane * 4);
;         if (pp) { const float* q = pp + j * 256 + lane * 4; v[j] = v[j] + ((*(const f32x4*)q + *(const f32x4*)(q + (size_t)NCTX * D)) + (*(const f32x4*)(q + (size_t)2 * NCTX * D) + *(const f32x4*)(q + (size_t)3 * NCTX * D))); *(f32x4*)(wb + j * 256 + lane * 4) = v[j]; }
;         ss += dot4(v[j]); }
;     ss = wave_sum(ss); const float rstd = rsqrtf(ss * (1.f / 1024.f) + EPS);
; #pragma unroll
;     for (int j = 0; j < 4; ++j) { const int col = j * 256 + lane * 4;
;         const f32x4 gv = *(const f32x4*)(g + col), sc = *(const f32x4*)(mp + scoff + col), sh = *(const f32x4*)(mp + shoff + col);
;         outv[j] = pk4(v[j] * rstd * gv * (sc + 1.f) + sh); }
; __device__ __forceinline__ void norm_rows(const float* xl, const float* xc, int nrows, const float* g, const float* modl, int shoff, int scoff, bf16_t* H, const float* part, float* xcw) {
;     const int tid = fresh_tid(), lane = tid & 63, gw = blockIdx.x * NWAVES + __builtin_amdgcn_readfirstlane(tid >> 6), ngw = gridDim.x * NWAVES;
;     for (int row_ = gw; row_ < nrows; row_ += ngw) { const int row = nrows - 1 - row_;
.LBB0_175:
	s_cmp_lg_u32 s24, 3
	s_cselect_b64 s[2:3], -1, 0
	v_writelane_b32 v255, s2, 13
	s_cmp_eq_u32 s24, 3
	v_readlane_b32 s4, v251, 0
	v_writelane_b32 v255, s3, 14
	s_cselect_b64 s[2:3], -1, 0
	v_writelane_b32 v255, s2, 15
	v_readlane_b32 s5, v251, 1
	v_readlane_b32 s6, v251, 2
	v_readlane_b32 s7, v251, 3
	v_readlane_b32 s8, v251, 4
	v_readlane_b32 s9, v251, 5
	v_writelane_b32 v255, s3, 16
	s_and_b64 s[2:3], s[2:3], exec
	v_readlane_b32 s10, v251, 6
	v_readlane_b32 s11, v251, 7
	s_mov_b64 s[4:5], s[8:9]
	s_cselect_b32 s2, s65, 0x11000
	s_mul_i32 s3, s24, 0x66000
	s_mov_b64 s[6:7], s[10:11]
	s_cselect_b32 s68, 0, s24
	v_writelane_b32 v255, s2, 17
	s_mul_hi_u32 s2, s24, 0x66000
	s_add_u32 s3, s6, s3
	v_writelane_b32 v255, s3, 18
	s_addc_u32 s2, s7, s2
	s_mov_b32 s25, s60
	v_writelane_b32 v255, s2, 19
	v_readlane_b32 s76, v252, 10
	v_readlane_b32 s2, v252, 32
	v_writelane_b32 v255, s24, 20
	s_cmp_eq_u32 s24, 0
	v_readlane_b32 s77, v252, 11
	v_readlane_b32 s80, v252, 14
	v_readlane_b32 s81, v252, 15
	v_readlane_b32 s3, v252, 33
	v_writelane_b32 v255, s25, 21
	s_cselect_b32 s25, s77, s5
	s_cselect_b32 s24, s76, s4
	s_cselect_b32 s37, s81, s3
	s_cselect_b32 s36, s80, s2
	s_cmp_lg_u32 s68, 0
	v_readlane_b32 s84, v252, 18
	s_cselect_b64 s[40:41], -1, 0
	v_readlane_b32 s84, v255, 12
	s_and_b64 vcc, exec, s[40:41]
	s_mov_b64 s[34:35], -1
	v_readlane_b32 s78, v252, 12
	v_readlane_b32 s79, v252, 13
	v_readlane_b32 s82, v252, 16
	v_readlane_b32 s83, v252, 17
	v_readlane_b32 s85, v252, 19
	v_readlane_b32 s86, v252, 20
	v_readlane_b32 s87, v252, 21
	v_readlane_b32 s88, v252, 22
	v_readlane_b32 s89, v252, 23
	v_readlane_b32 s90, v252, 24
	v_readlane_b32 s91, v252, 25
	s_cbranch_vccz .LBB0_184
	v_mov_b32_e32 v0, v216
	v_readlane_b32 s4, v255, 17
	v_readfirstlane_b32 s2, v0
	s_ashr_i32 s3, s2, 6
	s_add_i32 s2, s3, s20
	s_cmp_ge_i32 s2, s4
	s_cbranch_scc1 .LBB0_183
	v_readlane_b32 s4, v255, 20
	v_readlane_b32 s5, v255, 21
	v_lshlrev_b32_e32 v0, 2, v0
	s_lshl_b32 s8, s4, 10
	v_and_b32_e32 v0, 0xfc, v0
	v_readlane_b32 s4, v252, 38
	s_mov_b32 s9, s60
	v_readlane_b32 s76, v252, 10
	v_lshlrev_b32_e32 v194, 2, v0
	v_readlane_b32 s5, v252, 39
	s_lshl_b64 s[8:9], s[8:9], 2
	v_readlane_b32 s88, v252, 22
	v_lshl_add_u64 v[18:19], s[4:5], 0, v[194:195]
	v_readlane_b32 s4, v252, 32
	v_readlane_b32 s89, v252, 23
	s_add_u32 s8, s88, s8
	v_readlane_b32 s5, v252, 33
	s_addc_u32 s9, s89, s9
	v_readlane_b32 s84, v252, 18
	v_lshl_add_u64 v[20:21], s[4:5], 0, v[194:195]
	v_readlane_b32 s4, v254, 63
	v_readlane_b32 s5, v255, 17
	v_lshl_add_u64 v[16:17], s[8:9], 0, v[194:195]
	v_or_b32_e32 v2, 0x100, v0
	v_or_b32_e32 v4, 0x200, v0
	v_or_b32_e32 v6, 0x300, v0
	v_lshlrev_b32_e32 v194, 1, v0
	s_add_i32 s8, s4, s5
	v_readlane_b32 s84, v255, 12
	v_lshl_add_u64 v[22:23], s[72:73], 0, v[194:195]
	s_sub_i32 s34, s8, s3
	v_lshlrev_b32_e32 v30, 2, v0
	v_lshlrev_b32_e32 v31, 2, v2
	v_lshlrev_b32_e32 v32, 2, v4
	v_lshlrev_b32_e32 v33, 2, v6
	v_add_u32_e32 v90, 0x1000, v30
	v_add_u32_e32 v91, 0x1000, v31
	v_add_u32_e32 v92, 0x1000, v32
	v_add_u32_e32 v93, 0x1000, v33
	v_readlane_b32 s77, v252, 11
	v_readlane_b32 s78, v252, 12
	v_readlane_b32 s79, v252, 13
	v_readlane_b32 s80, v252, 14
	v_readlane_b32 s81, v252, 15
	v_readlane_b32 s82, v252, 16
	v_readlane_b32 s83, v252, 17
	v_readlane_b32 s85, v252, 19
	v_readlane_b32 s86, v252, 20
	v_readlane_b32 s87, v252, 21
	v_readlane_b32 s90, v252, 24
	v_readlane_b32 s91, v252, 25
	s_branch .LBB0_179

; __device__ __forceinline__ u32x2 pk4(f32x4 v) { u32x2 r; r.x = pk2(v[0], v[1]); r.y = pk2(v[2], v[3]); return r; }
; __device__ __forceinline__ float dot4(f32x4 v) { return (v[0] * v[0] + v[1] * v[1]) + (v[2] * v[2] + v[3] * v[3]); }
; __device__ __forceinline__ int fresh_tid() { int t = threadIdx.x; asm volatile("" : "+v"(t)); return t; }
; __device__ __forceinline__ void norm_row_compute(const float* xp, const float* g, const float* mp, int shoff, int scoff, int lane, u32x2 (&outv)[4], const float* pp = nullptr, float* wb = nullptr) {
;     f32x4 v[4]; float ss = 0.f;
; #pragma unroll
;     for (int j = 0; j < 4; ++j) { v[j] = *(const f32x4*)(xp + j * 256 + lane * 4);
;         if (pp) { const float* q = pp + j * 256 + lane * 4; v[j] = v[j] + ((*(const f32x4*)q + *(const f32x4*)(q + (size_t)NCTX * D)) + (*(const f32x4*)(q + (size_t)2 * NCTX * D) + *(const f32x4*)(q + (size_t)3 * NCTX * D))); *(f32x4*)(wb + j * 256 + lane * 4) = v[j]; }
;         ss += dot4(v[j]); }
;     ss = wave_sum(ss); const float rstd = rsqrtf(ss * (1.f / 1024.f) + EPS);
; #pragma unroll
;     for (int j = 0; j < 4; ++j) { const int col = j * 256 + lane * 4;
;         const f32x4 gv = *(const f32x4*)(g + col), sc = *(const f32x4*)(mp + scoff + col), sh = *(const f32x4*)(mp + shoff + col);
;         outv[j] = pk4(v[j] * rstd * gv * (sc + 1.f) + sh); }
; }
; __device__ __forceinline__ void norm_rows(const float* xl, const float* xc, int nrows, const float* g, const float* modl, int shoff, int scoff, bf16_t* H, const float* part, float* xcw) {
;     const int tid = fresh_tid(), lane = tid & 63, gw = blockIdx.x * NWAVES + __builtin_amdgcn_readfirstlane(tid >> 6), ngw = gridDim.x * NWAVES;
;     for (int row_ = gw; row_ < nrows; row_ += ngw) { const int row = nrows - 1 - row_;
;         const bool isctx = row >= NLAT; const int bidx = isctx ? BATCH : (row >> 12);
;         const float* xp = isctx ? xc + (size_t)(row - NLAT) * D : xl + (size_t)row * D;
;         u32x2 o[4];
;         if (isctx && part) norm_row_compute(xp, g, modl + bidx * MODROW, shoff, scoff, lane, o, part + (size_t)(row - NLAT) * D, xcw + (size_t)(row - NLAT) * D);
;         else norm_row_compute(xp, g, modl + bidx * MODROW, shoff, scoff, lane, o);
; #pragma unroll
;         for (int j = 0; j < 4; ++j) *(u32x2*)(H + (size_t)row * D + j * 256 + lane * 4) = o[j];
.LBB0_179:
	s_add_i32 s38, s34, 0x10000
	s_min_i32 s3, s38, 0x10000
	s_ashr_i32 s3, s3, 12
	s_ashr_i32 s39, s38, 31
	s_cmp_gt_i32 s38, 0xffff
	s_cselect_b32 s9, 0, s39
	s_cselect_b32 s8, s34, s38
	s_cselect_b32 s10, s37, s25
	s_cselect_b32 s11, s36, s24
	s_lshl_b64 s[8:9], s[8:9], 12
	s_add_u32 s44, s11, s8
	s_addc_u32 s45, s10, s9
	s_mov_b32 s35, s60
	s_cmp_lt_i32 s38, 0x10000
	s_mul_i32 s42, s3, 0x1800
	s_cbranch_scc0 .LBB0_181
	global_load_dwordx4 v[0:3], v30, s[44:45]
	global_load_dwordx4 v[4:7], v30, s[44:45] offset:1024
	global_load_dwordx4 v[8:11], v30, s[44:45] offset:2048
	global_load_dwordx4 v[12:15], v30, s[44:45] offset:3072
	s_ashr_i32 s43, s42, 31
	s_lshl_b64 s[8:9], s[42:43], 2
	v_readlane_b32 s100, v255, 18
	v_readlane_b32 s101, v255, 19
	s_add_u32 s100, s100, s8
	s_addc_u32 s101, s101, s9
	global_load_dwordx4 v[42:45], v[16:17], off
	global_load_dwordx4 v[46:49], v[16:17], off offset:1024
	global_load_dwordx4 v[50:53], v[16:17], off offset:2048
	global_load_dwordx4 v[54:57], v[16:17], off offset:3072
	global_load_dwordx4 v[58:61], v90, s[100:101]
	global_load_dwordx4 v[62:65], v91, s[100:101]
	global_load_dwordx4 v[66:69], v92, s[100:101]
	global_load_dwordx4 v[70:73], v93, s[100:101]
	global_load_dwordx4 v[74:77], v30, s[100:101]
	global_load_dwordx4 v[78:81], v30, s[100:101] offset:1024
	global_load_dwordx4 v[82:85], v30, s[100:101] offset:2048
	global_load_dwordx4 v[86:89], v30, s[100:101] offset:3072
	s_waitcnt vmcnt(12)
	v_pk_mul_f32 v[24:25], v[2:3], v[2:3]
	v_pk_mul_f32 v[26:27], v[0:1], v[0:1]
	s_nop 0
	v_pk_mov_b32 v[28:29], v[26:27], v[24:25] op_sel:[1,0]
	v_mov_b32_e32 v27, v25
	v_pk_add_f32 v[24:25], v[28:29], v[26:27]
	v_pk_mul_f32 v[26:27], v[6:7], v[6:7]
	v_pk_mul_f32 v[28:29], v[4:5], v[4:5]
	v_pk_add_f32 v[24:25], v[24:25], v[24:25] op_sel:[0,1] op_sel_hi:[1,0]
	v_pk_mov_b32 v[34:35], v[28:29], v[26:27] op_sel:[1,0]
	v_mov_b32_e32 v29, v27
	v_pk_add_f32 v[26:27], v[34:35], v[28:29]
	v_mul_f32_e32 v28, v12, v12
	v_mul_f32_e32 v29, v13, v13
	v_pk_add_f32 v[26:27], v[26:27], v[26:27] op_sel:[0,1] op_sel_hi:[1,0]
	v_mov_b32_e32 v25, v28
	v_mov_b32_e32 v27, v29
	v_pk_add_f32 v[24:25], v[24:25], v[26:27]
	v_mul_f32_e32 v26, v9, v9
	v_mul_f32_e32 v28, v11, v11
	v_mul_f32_e32 v34, v14, v14
	v_mul_f32_e32 v35, v15, v15
	v_pk_fma_f32 v[26:27], v[8:9], v[8:9], v[26:27] op_sel_hi:[1,1,0]
	v_pk_fma_f32 v[28:29], v[10:11], v[10:11], v[28:29] op_sel_hi:[1,1,0]
	v_mov_b32_e32 v27, v34
	v_mov_b32_e32 v29, v35
	v_pk_add_f32 v[26:27], v[26:27], v[28:29]
	s_nop 0
	v_pk_add_f32 v[24:25], v[24:25], v[26:27]
	s_nop 0
	v_add_f32_e32 v24, v24, v25
	s_nop 1
	v_add_f32_dpp v24, v24, v24 quad_perm:[1,0,3,2] row_mask:0xf bank_mask:0xf
	s_nop 1
	v_add_f32_dpp v24, v24, v24 quad_perm:[2,3,0,1] row_mask:0xf bank_mask:0xf
	s_nop 1
	v_add_f32_dpp v24, v24, v24 row_half_mirror row_mask:0xf bank_mask:0xf
	s_nop 1
	v_add_f32_dpp v24, v24, v24 row_mirror row_mask:0xf bank_mask:0xf
	v_mov_b32_e32 v25, v24
	s_nop 1
	v_permlane16_swap_b32_e32 v24, v25
	s_nop 1
	v_add_f32_e32 v24, v24, v25
	v_mov_b32_e32 v25, v24
	s_nop 1
	v_permlane32_swap_b32_e32 v24, v25
	s_nop 1
	v_add_f32_e32 v24, v24, v25
	v_mov_b32_e32 v25, 0
	s_branch .Lmix_fast
.Lmix_fast:
	v_fmamk_f32 v24, v24, 0x3a800000, v217
	v_cmp_gt_f32_e32 vcc, s66, v24
	v_mul_f32_e32 v25, 0x4b800000, v24
	s_lshl_b64 s[8:9], s[38:39], 11
	v_cndmask_b32_e32 v24, v24, v25, vcc
	v_rsq_f32_e32 v24, v24
	s_add_i32 s2, s2, s84
	s_sub_i32 s34, s34, s84
	v_readlane_b32 s3, v255, 17
	v_mul_f32_e32 v25, 0x45800000, v24
	v_cndmask_b32_e32 v24, v24, v25, vcc
	v_pk_mul_f32 v[0:1], v[0:1], v[24:25] op_sel_hi:[1,0]
	v_pk_mul_f32 v[2:3], v[2:3], v[24:25] op_sel_hi:[1,0]
	v_pk_mul_f32 v[4:5], v[4:5], v[24:25] op_sel_hi:[1,0]
	v_pk_mul_f32 v[6:7], v[6:7], v[24:25] op_sel_hi:[1,0]
	v_pk_mul_f32 v[8:9], v[8:9], v[24:25] op_sel_hi:[1,0]
	v_pk_mul_f32 v[10:11], v[10:11], v[24:25] op_sel_hi:[1,0]
	v_pk_mul_f32 v[12:13], v[12:13], v[24:25] op_sel_hi:[1,0]
	v_pk_mul_f32 v[14:15], v[14:15], v[24:25] op_sel_hi:[1,0]
	s_cmp_lt_i32 s2, s3
	s_waitcnt vmcnt(0)
	v_pk_mul_f32 v[0:1], v[42:43], v[0:1]
	v_pk_mul_f32 v[2:3], v[44:45], v[2:3]
	v_pk_add_f32 v[58:59], v[58:59], 1.0 op_sel_hi:[1,0]
	v_pk_add_f32 v[60:61], v[60:61], 1.0 op_sel_hi:[1,0]
	v_pk_fma_f32 v[0:1], v[58:59], v[0:1], v[74:75]
	v_pk_fma_f32 v[2:3], v[60:61], v[2:3], v[76:77]
	v_pk_mul_f32 v[4:5], v[46:47], v[4:5]
	v_pk_mul_f32 v[6:7], v[48:49], v[6:7]
	v_pk_add_f32 v[62:63], v[62:63], 1.0 op_sel_hi:[1,0]
	v_pk_add_f32 v[64:65], v[64:65], 1.0 op_sel_hi:[1,0]
	v_pk_fma_f32 v[4:5], v[62:63], v[4:5], v[78:79]
	v_pk_fma_f32 v[6:7], v[64:65], v[6:7], v[80:81]
	v_pk_mul_f32 v[8:9], v[50:51], v[8:9]
	v_pk_mul_f32 v[10:11], v[52:53], v[10:11]
	v_pk_add_f32 v[66:67], v[66:67], 1.0 op_sel_hi:[1,0]
	v_pk_add_f32 v[68:69], v[68:69], 1.0 op_sel_hi:[1,0]
	v_pk_fma_f32 v[8:9], v[66:67], v[8:9], v[82:83]
	v_pk_fma_f32 v[10:11], v[68:69], v[10:11], v[84:85]
	v_pk_mul_f32 v[12:13], v[54:55], v[12:13]
	v_pk_mul_f32 v[14:15], v[56:57], v[14:15]
	v_pk_add_f32 v[70:71], v[70:71], 1.0 op_sel_hi:[1,0]
	v_pk_add_f32 v[72:73], v[72:73], 1.0 op_sel_hi:[1,0]
	v_pk_fma_f32 v[12:13], v[70:71], v[12:13], v[86:87]
	v_pk_fma_f32 v[14:15], v[72:73], v[14:15], v[88:89]
	s_nop 0
	v_cvt_pk_bf16_f32 v0, v0, v1
	v_cvt_pk_bf16_f32 v1, v2, v3
	v_cvt_pk_bf16_f32 v2, v4, v5
	v_cvt_pk_bf16_f32 v3, v6, v7
	v_cvt_pk_bf16_f32 v4, v8, v9
	v_cvt_pk_bf16_f32 v5, v10, v11
	v_cvt_pk_bf16_f32 v6, v12, v13
	v_cvt_pk_bf16_f32 v7, v14, v15
	v_lshl_add_u64 v[26:27], v[22:23], 0, s[8:9]
	global_store_dwordx2 v[26:27], v[0:1], off
	global_store_dwordx2 v[26:27], v[2:3], off offset:512
	global_store_dwordx2 v[26:27], v[4:5], off offset:1024
	global_store_dwordx2 v[26:27], v[6:7], off offset:1536
	s_cbranch_scc0 .LBB0_183
	s_branch .LBB0_179

; __device__ __forceinline__ float dot4(f32x4 v) { return (v[0] * v[0] + v[1] * v[1]) + (v[2] * v[2] + v[3] * v[3]); }
; __device__ __forceinline__ void norm_row_compute(const float* xp, const float* g, const float* mp, int shoff, int scoff, int lane, u32x2 (&outv)[4], const float* pp = nullptr, float* wb = nullptr) {
;     ...
;         if (pp) { const float* q = pp + j * 256 + lane * 4; v[j] = v[j] + ((*(const f32x4*)q + *(const f32x4*)(q + (size_t)NCTX * D)) + (*(const f32x4*)(q + (size_t)2 * NCTX * D) + *(const f32x4*)(q + (size_t)3 * NCTX * D))); *(f32x4*)(wb + j * 256 + lane * 4) = v[j]; }
;         ss += dot4(v[j]); }
;     ss = wave_sum(ss); const float rstd = rsqrtf(ss * (1.f / 1024.f) + EPS);
; __device__ __forceinline__ void norm_rows(const float* xl, const float* xc, int nrows, const float* g, const float* modl, int shoff, int scoff, bf16_t* H, const float* part, float* xcw) {
;     ...
;         if (isctx && part) norm_row_compute(xp, g, modl + bidx * MODROW, shoff, scoff, lane, o, part + (size_t)(row - NLAT) * D, xcw + (size_t)(row - NLAT) * D);
.LBB0_182:
	s_lshl_b64 s[8:9], s[34:35], 12
	v_lshl_add_u64 v[12:13], v[18:19], 0, s[8:9]
	v_add_co_u32_e32 v14, vcc, 0x1000000, v12
	global_load_dwordx4 v[0:3], v30, s[44:45]
	global_load_dwordx4 v[4:7], v[12:13], off
	v_addc_co_u32_e32 v15, vcc, 0, v13, vcc
	global_load_dwordx4 v[8:11], v[14:15], off
	v_add_co_u32_e32 v26, vcc, 0x2000000, v12
	s_waitcnt lgkmcnt(0)
	v_lshl_add_u64 v[24:25], v[20:21], 0, s[8:9]
	v_addc_co_u32_e32 v27, vcc, 0, v13, vcc
	v_add_co_u32_e32 v28, vcc, 0x3000000, v12
	s_waitcnt vmcnt(0)
	v_pk_add_f32 v[34:35], v[6:7], v[10:11]
	v_addc_co_u32_e32 v29, vcc, 0, v13, vcc
	v_pk_add_f32 v[36:37], v[4:5], v[8:9]
	global_load_dwordx4 v[4:7], v[26:27], off
	global_load_dwordx4 v[8:11], v[28:29], off
	v_cmp_lt_i32_e32 vcc, v226, v220
	s_waitcnt vmcnt(0)
	v_pk_add_f32 v[6:7], v[6:7], v[10:11]
	v_pk_add_f32 v[4:5], v[4:5], v[8:9]
	v_pk_add_f32 v[6:7], v[34:35], v[6:7]
	v_pk_add_f32 v[4:5], v[36:37], v[4:5]
	v_pk_add_f32 v[2:3], v[2:3], v[6:7]
	v_pk_add_f32 v[0:1], v[0:1], v[4:5]
	global_store_dwordx4 v[24:25], v[0:3], off
	global_load_dwordx4 v[4:7], v30, s[44:45] offset:1024
	global_load_dwordx4 v[8:11], v[12:13], off offset:1024
	global_load_dwordx4 v[34:37], v[14:15], off offset:1024
	s_waitcnt vmcnt(0)
	v_pk_add_f32 v[38:39], v[10:11], v[36:37]
	v_pk_add_f32 v[40:41], v[8:9], v[34:35]
	global_load_dwordx4 v[8:11], v[26:27], off offset:1024
	global_load_dwordx4 v[34:37], v[28:29], off offset:1024
	s_waitcnt vmcnt(0)
	v_pk_add_f32 v[10:11], v[10:11], v[36:37]
	v_pk_add_f32 v[8:9], v[8:9], v[34:35]
	v_pk_add_f32 v[10:11], v[38:39], v[10:11]
	v_pk_add_f32 v[8:9], v[40:41], v[8:9]
	v_pk_add_f32 v[6:7], v[6:7], v[10:11]
	v_pk_add_f32 v[4:5], v[4:5], v[8:9]
	global_store_dwordx4 v[24:25], v[4:7], off offset:1024
	global_load_dwordx4 v[8:11], v30, s[44:45] offset:2048
	global_load_dwordx4 v[34:37], v[12:13], off offset:2048
	global_load_dwordx4 v[38:41], v[14:15], off offset:2048
	s_waitcnt vmcnt(0)
	v_pk_add_f32 v[42:43], v[36:37], v[40:41]
	v_pk_add_f32 v[44:45], v[34:35], v[38:39]
	global_load_dwordx4 v[34:37], v[26:27], off offset:2048
	global_load_dwordx4 v[38:41], v[28:29], off offset:2048
	s_waitcnt vmcnt(0)
	v_pk_add_f32 v[36:37], v[36:37], v[40:41]
	v_pk_add_f32 v[34:35], v[34:35], v[38:39]
	v_pk_add_f32 v[36:37], v[42:43], v[36:37]
	v_pk_add_f32 v[34:35], v[44:45], v[34:35]
	v_pk_add_f32 v[10:11], v[10:11], v[36:37]
	v_pk_add_f32 v[8:9], v[8:9], v[34:35]
	global_store_dwordx4 v[24:25], v[8:11], off offset:2048
	global_load_dwordx4 v[34:37], v30, s[44:45] offset:3072
	global_load_dwordx4 v[38:41], v[12:13], off offset:3072
	s_nop 0
	global_load_dwordx4 v[12:15], v[14:15], off offset:3072
	s_waitcnt vmcnt(0)
	v_pk_add_f32 v[40:41], v[40:41], v[14:15]
	v_pk_add_f32 v[38:39], v[38:39], v[12:13]
	global_load_dwordx4 v[12:15], v[26:27], off offset:3072
	s_nop 0
	global_load_dwordx4 v[26:29], v[28:29], off offset:3072
	s_waitcnt vmcnt(0)
	v_pk_add_f32 v[14:15], v[14:15], v[28:29]
	v_pk_add_f32 v[12:13], v[12:13], v[26:27]
	v_pk_add_f32 v[14:15], v[40:41], v[14:15]
	v_pk_add_f32 v[12:13], v[38:39], v[12:13]
	v_pk_add_f32 v[14:15], v[36:37], v[14:15]
	v_pk_add_f32 v[12:13], v[34:35], v[12:13]
	global_store_dwordx4 v[24:25], v[12:15], off offset:3072
	v_pk_mul_f32 v[24:25], v[2:3], v[2:3]
	v_pk_mul_f32 v[26:27], v[0:1], v[0:1]
	s_nop 0
	v_pk_mov_b32 v[28:29], v[26:27], v[24:25] op_sel:[1,0]
	v_mov_b32_e32 v27, v25
	v_pk_add_f32 v[24:25], v[28:29], v[26:27]
	v_pk_mul_f32 v[26:27], v[6:7], v[6:7]
	v_pk_mul_f32 v[28:29], v[4:5], v[4:5]
	v_pk_add_f32 v[24:25], v[24:25], v[24:25] op_sel:[0,1] op_sel_hi:[1,0]
	v_pk_mov_b32 v[34:35], v[28:29], v[26:27] op_sel:[1,0]
	v_mov_b32_e32 v29, v27
	v_pk_add_f32 v[26:27], v[34:35], v[28:29]
	v_mul_f32_e32 v28, v12, v12
	v_mul_f32_e32 v29, v13, v13
	v_pk_add_f32 v[26:27], v[26:27], v[26:27] op_sel:[0,1] op_sel_hi:[1,0]
	v_mov_b32_e32 v25, v28
	v_mov_b32_e32 v27, v29
	v_pk_add_f32 v[24:25], v[24:25], v[26:27]
	v_mul_f32_e32 v26, v9, v9
	v_mul_f32_e32 v28, v11, v11
	v_mul_f32_e32 v34, v14, v14
	v_mul_f32_e32 v35, v15, v15
	v_pk_fma_f32 v[26:27], v[8:9], v[8:9], v[26:27] op_sel_hi:[1,1,0]
	v_pk_fma_f32 v[28:29], v[10:11], v[10:11], v[28:29] op_sel_hi:[1,1,0]
	v_mov_b32_e32 v27, v34
	v_mov_b32_e32 v29, v35
	v_pk_add_f32 v[26:27], v[26:27], v[28:29]
	s_nop 0
	v_pk_add_f32 v[24:25], v[24:25], v[26:27]
	s_nop 0
	v_add_f32_e32 v24, v24, v25
	v_cndmask_b32_e32 v25, v219, v226, vcc
	v_lshlrev_b32_e32 v25, 2, v25
	s_nop 1
	v_add_f32_dpp v24, v24, v24 quad_perm:[1,0,3,2] row_mask:0xf bank_mask:0xf
	s_nop 1
	v_add_f32_dpp v24, v24, v24 quad_perm:[2,3,0,1] row_mask:0xf bank_mask:0xf
	s_nop 1
	v_add_f32_dpp v24, v24, v24 row_half_mirror row_mask:0xf bank_mask:0xf
	s_nop 1
	v_add_f32_dpp v24, v24, v24 row_mirror row_mask:0xf bank_mask:0xf
	v_mov_b32_e32 v25, v24
	s_nop 1
	v_permlane16_swap_b32_e32 v24, v25
	s_nop 1
	v_add_f32_e32 v24, v24, v25
	v_mov_b32_e32 v25, v24
	s_nop 1
	v_permlane32_swap_b32_e32 v24, v25
	s_nop 1
	v_add_f32_e32 v24, v24, v25
	v_mov_b32_e32 v25, 0
	s_branch .LBB0_178

; #define LAS __attribute__((address_space(3)))
; __device__ __forceinline__ u32x2 pk4(f32x4 v) { u32x2 r; r.x = pk2(v[0], v[1]); r.y = pk2(v[2], v[3]); return r; }
; __device__ __forceinline__ float dot4(f32x4 v) { return (v[0] * v[0] + v[1] * v[1]) + (v[2] * v[2] + v[3] * v[3]); }
; __device__ __forceinline__ void norm_row_compute(const float* xp, const float* g, const float* mp, int shoff, int scoff, int lane, u32x2 (&outv)[4], const float* pp = nullptr, float* wb = nullptr) {
;     f32x4 v[4]; float ss = 0.f;
; #pragma unroll
;     for (int j = 0; j < 4; ++j) { v[j] = *(const f32x4*)(xp + j * 256 + lane * 4);
;         if (pp) { const float* q = pp + j * 256 + lane * 4; v[j] = v[j] + ((*(const f32x4*)q + *(const f32x4*)(q + (size_t)NCTX * D)) + (*(const f32x4*)(q + (size_t)2 * NCTX * D) + *(const f32x4*)(q + (size_t)3 * NCTX * D))); *(f32x4*)(wb + j * 256 + lane * 4) = v[j]; }
;         ss += dot4(v[j]); }
;     ss = wave_sum(ss); const float rstd = rsqrtf(ss * (1.f / 1024.f) + EPS);
; #pragma unroll
;     for (int j = 0; j < 4; ++j) { const int col = j * 256 + lane * 4;
;         const f32x4 gv = *(const f32x4*)(g + col), sc = *(const f32x4*)(mp + scoff + col), sh = *(const f32x4*)(mp + shoff + col);
;         outv[j] = pk4(v[j] * rstd * gv * (sc + 1.f) + sh); }
; __device__ __forceinline__ void norm_rows_T(LAS unsigned char* lds, const float* xl, const float* xc, int nrows, const float* g, const float* modl, int shoff, int scoff, bf16_t* HT, float* hN, float* NYQ) {
;     ...
;         for (int i = 0; i < 8; ++i) { const int slot = wid * 8 + i;
;             const float* xp;
;             if (isctx) xp = xc + (size_t)(b * CTX + s0 + slot) * D;
;             else { int tok = slot < 32 ? s0 + slot : SEQ - (s0 + slot - 32); if (s0 == 0 && slot == 32) tok = SEQ / 2; xp = xl + (size_t)(b * SEQ + tok) * D; }
;             u32x2 o[4]; norm_row_compute(xp, g, modl + bidx * MODROW, shoff, scoff, lane, o);
; #pragma unroll
;             for (int j = 0; j < 4; ++j) *(LAS u32x2*)(tl + slot * 1028 + j * 256 + lane * 4) = o[j]; }
.LBB0_193:
	s_ashr_i32 s49, s48, 31
	s_lshl_b64 s[28:29], s[48:49], 12
	s_add_u32 s28, s52, s28
	s_addc_u32 s29, s53, s29
	global_load_dwordx4 v[200:203], v214, s[28:29]
	global_load_dwordx4 v[230:233], v214, s[28:29] offset:1024
	global_load_dwordx4 v[234:237], v214, s[28:29] offset:2048
	global_load_dwordx4 v[238:241], v214, s[28:29] offset:3072
	s_add_i32 s12, s12, 1
	s_add_i32 s15, s15, -1
	s_cmp_eq_u32 s12, 8
	s_waitcnt vmcnt(0)
	v_pk_mul_f32 v[242:243], v[202:203], v[202:203]
	v_pk_mul_f32 v[244:245], v[200:201], v[200:201]
	s_nop 0
	v_pk_mov_b32 v[246:247], v[244:245], v[242:243] op_sel:[1,0]
	v_mov_b32_e32 v245, v243
	v_pk_add_f32 v[242:243], v[246:247], v[244:245]
	v_pk_mul_f32 v[244:245], v[232:233], v[232:233]
	v_pk_mul_f32 v[246:247], v[230:231], v[230:231]
	v_pk_add_f32 v[242:243], v[242:243], v[242:243] op_sel:[0,1] op_sel_hi:[1,0]
	v_pk_mov_b32 v[248:249], v[246:247], v[244:245] op_sel:[1,0]
	v_mov_b32_e32 v247, v245
	v_pk_add_f32 v[244:245], v[248:249], v[246:247]
	v_mul_f32_e32 v246, v238, v238
	v_mul_f32_e32 v247, v239, v239
	v_pk_add_f32 v[244:245], v[244:245], v[244:245] op_sel:[0,1] op_sel_hi:[1,0]
	v_mov_b32_e32 v243, v246
	v_mov_b32_e32 v245, v247
	v_pk_add_f32 v[242:243], v[242:243], v[244:245]
	v_mul_f32_e32 v244, v235, v235
	v_mul_f32_e32 v246, v237, v237
	v_mul_f32_e32 v248, v240, v240
	v_mul_f32_e32 v249, v241, v241
	v_pk_fma_f32 v[244:245], v[234:235], v[234:235], v[244:245] op_sel_hi:[1,1,0]
	v_pk_fma_f32 v[246:247], v[236:237], v[236:237], v[246:247] op_sel_hi:[1,1,0]
	v_mov_b32_e32 v245, v248
	v_mov_b32_e32 v247, v249
	v_pk_add_f32 v[244:245], v[244:245], v[246:247]
	s_nop 0
	v_pk_add_f32 v[242:243], v[242:243], v[244:245]
	s_nop 0
	v_add_f32_e32 v242, v242, v243
	s_nop 1
	v_add_f32_dpp v242, v242, v242 quad_perm:[1,0,3,2] row_mask:0xf bank_mask:0xf
	s_nop 1
	v_add_f32_dpp v242, v242, v242 quad_perm:[2,3,0,1] row_mask:0xf bank_mask:0xf
	s_nop 1
	v_add_f32_dpp v242, v242, v242 row_half_mirror row_mask:0xf bank_mask:0xf
	s_nop 1
	v_add_f32_dpp v242, v242, v242 row_mirror row_mask:0xf bank_mask:0xf
	v_mov_b32_e32 v243, v242
	s_nop 1
	v_permlane16_swap_b32_e32 v242, v243
	s_nop 1
	v_add_f32_e32 v242, v242, v243
	v_mov_b32_e32 v243, v242
	s_nop 1
	v_permlane32_swap_b32_e32 v242, v243
	s_nop 1
	v_add_f32_e32 v242, v242, v243
	v_fmamk_f32 v242, v242, 0x3a800000, v217
	v_cmp_gt_f32_e32 vcc, s66, v242
	v_mul_f32_e32 v243, 0x4b800000, v242
	s_nop 0
	v_cndmask_b32_e32 v242, v242, v243, vcc
	v_rsq_f32_e32 v242, v242
	s_nop 0
	v_mul_f32_e32 v243, 0x45800000, v242
	v_cndmask_b32_e32 v242, v242, v243, vcc
	v_pk_mul_f32 v[202:203], v[202:203], v[242:243] op_sel_hi:[1,0]
	v_pk_mul_f32 v[200:201], v[200:201], v[242:243] op_sel_hi:[1,0]
	v_pk_mul_f32 v[202:203], v[2:3], v[202:203]
	v_pk_mul_f32 v[200:201], v[0:1], v[200:201]
	v_pk_fma_f32 v[202:203], v[100:101], v[202:203], v[10:11]
	v_pk_fma_f32 v[200:201], v[102:103], v[200:201], v[8:9]
	v_pk_mul_f32 v[230:231], v[230:231], v[242:243] op_sel_hi:[1,0]
	v_cvt_pk_bf16_f32 v200, v200, v201
	v_cvt_pk_bf16_f32 v201, v202, v203
	v_pk_mul_f32 v[202:203], v[232:233], v[242:243] op_sel_hi:[1,0]
	v_pk_mul_f32 v[230:231], v[4:5], v[230:231]
	v_pk_mul_f32 v[202:203], v[6:7], v[202:203]
	v_pk_fma_f32 v[230:231], v[106:107], v[230:231], v[12:13]
	v_pk_fma_f32 v[202:203], v[104:105], v[202:203], v[14:15]
	v_cvt_pk_bf16_f32 v230, v230, v231
	v_cvt_pk_bf16_f32 v231, v202, v203
	v_pk_mul_f32 v[202:203], v[236:237], v[242:243] op_sel_hi:[1,0]
	v_pk_mul_f32 v[232:233], v[234:235], v[242:243] op_sel_hi:[1,0]
	v_pk_mul_f32 v[202:203], v[18:19], v[202:203]
	v_pk_mul_f32 v[232:233], v[16:17], v[232:233]
	v_pk_fma_f32 v[202:203], v[108:109], v[202:203], v[26:27]
	v_pk_fma_f32 v[232:233], v[110:111], v[232:233], v[24:25]
	v_pk_mul_f32 v[234:235], v[238:239], v[242:243] op_sel_hi:[1,0]
	v_cvt_pk_bf16_f32 v232, v232, v233
	v_cvt_pk_bf16_f32 v233, v202, v203
	v_pk_mul_f32 v[202:203], v[240:241], v[242:243] op_sel_hi:[1,0]
	v_pk_mul_f32 v[234:235], v[20:21], v[234:235]
	v_pk_mul_f32 v[202:203], v[22:23], v[202:203]
	v_pk_fma_f32 v[234:235], v[114:115], v[234:235], v[28:29]
	v_pk_fma_f32 v[202:203], v[112:113], v[202:203], v[30:31]
	v_cvt_pk_bf16_f32 v234, v234, v235
	v_cvt_pk_bf16_f32 v235, v202, v203
	ds_write2st64_b64 v99, v[200:201], v[230:231] offset1:1
	ds_write2st64_b64 v99, v[232:233], v[234:235] offset0:2 offset1:3
	v_add_u32_e32 v99, 0x808, v99
	s_cbranch_scc1 .LBB0_198

; __device__ __forceinline__ int fresh_tid() { int t = threadIdx.x; asm volatile("" : "+v"(t)); return t; }
; __device__ __forceinline__ void norm_rows(const float* xl, const float* xc, int nrows, const float* g, const float* modl, int shoff, int scoff, bf16_t* H, const float* part, float* xcw) {
;     const int tid = fresh_tid(), lane = tid & 63, gw = blockIdx.x * NWAVES + __builtin_amdgcn_readfirstlane(tid >> 6), ngw = gridDim.x * NWAVES;
;     for (int row_ = gw; row_ < nrows; row_ += ngw) { const int row = nrows - 1 - row_;
; __global__ void __launch_bounds__(512, 2) fwd_megakernel(Args a) {
;     ...
;         norm_rows(out, xc, nrows, norm_mlp_g + l * D, MODl, 3072, 4096, H, wctx ? PART : nullptr, XC);
.LBB0_1556:
	s_or_b64 exec, exec, s[6:7]
	s_waitcnt lgkmcnt(0)
	v_mov_b32_e32 v0, v216
	s_barrier
	v_readlane_b32 s4, v255, 17
	v_readfirstlane_b32 s2, v0
	s_ashr_i32 s3, s2, 6
	s_add_i32 s2, s3, s20
	s_cmp_ge_i32 s2, s4
	s_cbranch_scc1 .LBB0_1564
	s_lshl_b32 s6, s24, 10
	s_mov_b32 s7, s60
	v_readlane_b32 s76, v252, 10
	s_lshl_b64 s[6:7], s[6:7], 2
	v_readlane_b32 s90, v252, 24
	v_lshlrev_b32_e32 v0, 2, v0
	v_readlane_b32 s91, v252, 25
	s_add_u32 s8, s90, s6
	v_and_b32_e32 v0, 0xfc, v0
	v_readlane_b32 s4, v252, 32
	s_addc_u32 s9, s91, s7
	v_lshlrev_b32_e32 v194, 2, v0
	v_readlane_b32 s5, v252, 33
	s_cmp_lg_u64 s[44:45], 0
	v_readlane_b32 s84, v252, 18
	v_lshl_add_u64 v[20:21], s[4:5], 0, v[194:195]
	v_readlane_b32 s4, v254, 63
	v_readlane_b32 s5, v255, 17
	s_cselect_b64 s[6:7], -1, 0
	v_lshl_add_u64 v[16:17], s[8:9], 0, v[194:195]
	v_or_b32_e32 v2, 0x100, v0
	v_or_b32_e32 v4, 0x200, v0
	v_or_b32_e32 v6, 0x300, v0
	v_lshl_add_u64 v[18:19], s[44:45], 0, v[194:195]
	v_lshlrev_b32_e32 v194, 1, v0
	s_add_i32 s8, s4, s5
	v_readlane_b32 s84, v255, 12
	v_lshl_add_u64 v[22:23], s[72:73], 0, v[194:195]
	s_sub_i32 s34, s8, s3
	v_lshlrev_b32_e32 v25, 2, v0
	v_lshlrev_b32_e32 v26, 2, v2
	v_lshlrev_b32_e32 v27, 2, v4
	v_lshlrev_b32_e32 v28, 2, v6
	v_add_u32_e32 v94, 0x4000, v25
	v_add_u32_e32 v95, 0x4000, v26
	v_add_u32_e32 v96, 0x4000, v27
	v_add_u32_e32 v97, 0x4000, v28
	v_add_u32_e32 v98, 0x3000, v25
	v_add_u32_e32 v99, 0x3000, v26
	v_add_u32_e32 v100, 0x3000, v27
	v_add_u32_e32 v101, 0x3000, v28
	v_readlane_b32 s77, v252, 11
	v_readlane_b32 s78, v252, 12
	v_readlane_b32 s79, v252, 13
	v_readlane_b32 s80, v252, 14
	v_readlane_b32 s81, v252, 15
	v_readlane_b32 s82, v252, 16
	v_readlane_b32 s83, v252, 17
	v_readlane_b32 s85, v252, 19
	v_readlane_b32 s86, v252, 20
	v_readlane_b32 s87, v252, 21
	v_readlane_b32 s88, v252, 22
	v_readlane_b32 s89, v252, 23
	s_branch .LBB0_1559

; __device__ __forceinline__ u32x2 pk4(f32x4 v) { u32x2 r; r.x = pk2(v[0], v[1]); r.y = pk2(v[2], v[3]); return r; }
; __device__ __forceinline__ float dot4(f32x4 v) { return (v[0] * v[0] + v[1] * v[1]) + (v[2] * v[2] + v[3] * v[3]); }
; __device__ __forceinline__ int fresh_tid() { int t = threadIdx.x; asm volatile("" : "+v"(t)); return t; }
; __device__ __forceinline__ void norm_row_compute(const float* xp, const float* g, const float* mp, int shoff, int scoff, int lane, u32x2 (&outv)[4], const float* pp = nullptr, float* wb = nullptr) {
;     f32x4 v[4]; float ss = 0.f;
; #pragma unroll
;     for (int j = 0; j < 4; ++j) { v[j] = *(const f32x4*)(xp + j * 256 + lane * 4);
;         if (pp) { const float* q = pp + j * 256 + lane * 4; v[j] = v[j] + ((*(const f32x4*)q + *(const f32x4*)(q + (size_t)NCTX * D)) + (*(const f32x4*)(q + (size_t)2 * NCTX * D) + *(const f32x4*)(q + (size_t)3 * NCTX * D))); *(f32x4*)(wb + j * 256 + lane * 4) = v[j]; }
;         ss += dot4(v[j]); }
;     ss = wave_sum(ss); const float rstd = rsqrtf(ss * (1.f / 1024.f) + EPS);
; #pragma unroll
;     for (int j = 0; j < 4; ++j) { const int col = j * 256 + lane * 4;
;         const f32x4 gv = *(const f32x4*)(g + col), sc = *(const f32x4*)(mp + scoff + col), sh = *(const f32x4*)(mp + shoff + col);
;         outv[j] = pk4(v[j] * rstd * gv * (sc + 1.f) + sh); }
; }
; __device__ __forceinline__ void norm_rows(const float* xl, const float* xc, int nrows, const float* g, const float* modl, int shoff, int scoff, bf16_t* H, const float* part, float* xcw) {
;     const int tid = fresh_tid(), lane = tid & 63, gw = blockIdx.x * NWAVES + __builtin_amdgcn_readfirstlane(tid >> 6), ngw = gridDim.x * NWAVES;
;     for (int row_ = gw; row_ < nrows; row_ += ngw) { const int row = nrows - 1 - row_;
;         const bool isctx = row >= NLAT; const int bidx = isctx ? BATCH : (row >> 12);
;         const float* xp = isctx ? xc + (size_t)(row - NLAT) * D : xl + (size_t)row * D;
;         u32x2 o[4];
;         if (isctx && part) norm_row_compute(xp, g, modl + bidx * MODROW, shoff, scoff, lane, o, part + (size_t)(row - NLAT) * D, xcw + (size_t)(row - NLAT) * D);
;         else norm_row_compute(xp, g, modl + bidx * MODROW, shoff, scoff, lane, o);
; #pragma unroll
;         for (int j = 0; j < 4; ++j) *(u32x2*)(H + (size_t)row * D + j * 256 + lane * 4) = o[j];
.LBB0_1559:
	s_add_i32 s44, s34, 0x10000
	s_min_i32 s3, s44, 0x10000
	s_ashr_i32 s3, s3, 12
	s_ashr_i32 s45, s44, 31
	s_cmp_gt_i32 s44, 0xffff
	s_cselect_b64 s[8:9], -1, 0
	s_and_b64 s[10:11], s[8:9], exec
	v_readlane_b32 s12, v251, 0
	s_cselect_b32 s11, 0, s45
	s_cselect_b32 s10, s34, s44
	v_readlane_b32 s13, v251, 1
	v_readlane_b32 s16, v251, 4
	v_readlane_b32 s17, v251, 5
	s_cselect_b32 s12, s37, s17
	s_cselect_b32 s13, s36, s16
	s_lshl_b64 s[10:11], s[10:11], 12
	s_add_u32 s48, s13, s10
	s_addc_u32 s49, s12, s11
	s_and_b64 s[8:9], s[6:7], s[8:9]
	s_mov_b32 s35, s60
	s_andn2_b64 vcc, exec, s[8:9]
	s_mul_i32 s46, s3, 0x1800
	v_readlane_b32 s14, v251, 2
	v_readlane_b32 s15, v251, 3
	v_readlane_b32 s18, v251, 6
	v_readlane_b32 s19, v251, 7
	s_cbranch_vccz .LBB0_1561
	global_load_dwordx4 v[12:15], v25, s[48:49]
	global_load_dwordx4 v[8:11], v25, s[48:49] offset:1024
	global_load_dwordx4 v[4:7], v25, s[48:49] offset:2048
	global_load_dwordx4 v[0:3], v25, s[48:49] offset:3072
	v_cmp_lt_i32_e32 vcc, v226, v220
	s_ashr_i32 s47, s46, 31
	s_lshl_b64 s[8:9], s[46:47], 2
	v_readlane_b32 s100, v255, 18
	v_readlane_b32 s101, v255, 19
	s_add_u32 s100, s100, s8
	s_addc_u32 s101, s101, s9
	global_load_dwordx4 v[42:45], v[16:17], off
	global_load_dwordx4 v[46:49], v[16:17], off offset:1024
	global_load_dwordx4 v[50:53], v[16:17], off offset:2048
	global_load_dwordx4 v[54:57], v[16:17], off offset:3072
	global_load_dwordx4 v[58:61], v94, s[100:101]
	global_load_dwordx4 v[62:65], v95, s[100:101]
	global_load_dwordx4 v[66:69], v96, s[100:101]
	global_load_dwordx4 v[70:73], v97, s[100:101]
	global_load_dwordx4 v[74:77], v98, s[100:101]
	global_load_dwordx4 v[78:81], v99, s[100:101]
	global_load_dwordx4 v[82:85], v100, s[100:101]
	global_load_dwordx4 v[86:89], v101, s[100:101]
	s_waitcnt vmcnt(15)
	v_pk_mul_f32 v[30:31], v[14:15], v[14:15]
	v_pk_mul_f32 v[32:33], v[12:13], v[12:13]
	s_waitcnt vmcnt(12)
	v_mul_f32_e32 v24, v0, v0
	v_pk_mov_b32 v[34:35], v[32:33], v[30:31] op_sel:[1,0]
	v_mov_b32_e32 v33, v31
	v_pk_add_f32 v[30:31], v[34:35], v[32:33]
	v_pk_mul_f32 v[32:33], v[10:11], v[10:11]
	v_pk_mul_f32 v[34:35], v[8:9], v[8:9]
	v_mul_f32_e32 v29, v1, v1
	v_pk_mov_b32 v[36:37], v[34:35], v[32:33] op_sel:[1,0]
	v_mov_b32_e32 v35, v33
	v_pk_add_f32 v[32:33], v[36:37], v[34:35]
	v_pk_add_f32 v[30:31], v[30:31], v[30:31] op_sel:[0,1] op_sel_hi:[1,0]
	v_pk_add_f32 v[32:33], v[32:33], v[32:33] op_sel:[0,1] op_sel_hi:[1,0]
	v_mov_b32_e32 v31, v24
	v_mov_b32_e32 v33, v29
	v_mul_f32_e32 v24, v5, v5
	v_mul_f32_e32 v34, v2, v2
	v_pk_add_f32 v[30:31], v[30:31], v[32:33]
	v_pk_fma_f32 v[32:33], v[4:5], v[4:5], v[24:25] op_sel_hi:[1,1,0]
	v_mul_f32_e32 v24, v7, v7
	v_mul_f32_e32 v36, v3, v3
	v_mov_b32_e32 v33, v34
	v_pk_fma_f32 v[34:35], v[6:7], v[6:7], v[24:25] op_sel_hi:[1,1,0]
	v_cndmask_b32_e32 v29, v219, v226, vcc
	v_mov_b32_e32 v35, v36
	v_pk_add_f32 v[32:33], v[32:33], v[34:35]
	v_lshlrev_b32_e32 v29, 2, v29
	v_pk_add_f32 v[30:31], v[30:31], v[32:33]
	v_cmp_lt_i32_e32 vcc, v225, v220
	v_add_f32_e32 v24, v30, v31
	s_nop 1
	v_add_f32_dpp v24, v24, v24 quad_perm:[1,0,3,2] row_mask:0xf bank_mask:0xf
	s_nop 1
	v_add_f32_dpp v24, v24, v24 quad_perm:[2,3,0,1] row_mask:0xf bank_mask:0xf
	s_nop 1
	v_add_f32_dpp v24, v24, v24 row_half_mirror row_mask:0xf bank_mask:0xf
	s_nop 1
	v_add_f32_dpp v24, v24, v24 row_mirror row_mask:0xf bank_mask:0xf
	v_mov_b32_e32 v29, v24
	s_nop 1
	v_permlane16_swap_b32_e32 v24, v29
	s_nop 1
	v_add_f32_e32 v24, v24, v29
	v_mov_b32_e32 v29, v24
	s_nop 1
	v_permlane32_swap_b32_e32 v24, v29
	s_nop 1
	v_add_f32_e32 v24, v24, v29
	v_mov_b32_e32 v29, 0
	s_branch .Lmlp_fast
.Lmlp_fast:
	v_fmamk_f32 v24, v24, 0x3a800000, v217
	v_cmp_gt_f32_e32 vcc, s66, v24
	v_mul_f32_e32 v29, 0x4b800000, v24
	s_lshl_b64 s[8:9], s[44:45], 11
	v_cndmask_b32_e32 v24, v24, v29, vcc
	v_rsq_f32_e32 v24, v24
	s_add_i32 s2, s2, s84
	s_sub_i32 s34, s34, s84
	v_readlane_b32 s3, v255, 17
	v_mul_f32_e32 v29, 0x45800000, v24
	v_cndmask_b32_e32 v24, v24, v29, vcc
	v_pk_mul_f32 v[0:1], v[0:1], v[24:25] op_sel_hi:[1,0]
	v_pk_mul_f32 v[2:3], v[2:3], v[24:25] op_sel_hi:[1,0]
	v_pk_mul_f32 v[4:5], v[4:5], v[24:25] op_sel_hi:[1,0]
	v_pk_mul_f32 v[6:7], v[6:7], v[24:25] op_sel_hi:[1,0]
	v_pk_mul_f32 v[8:9], v[8:9], v[24:25] op_sel_hi:[1,0]
	v_pk_mul_f32 v[10:11], v[10:11], v[24:25] op_sel_hi:[1,0]
	v_pk_mul_f32 v[12:13], v[12:13], v[24:25] op_sel_hi:[1,0]
	v_pk_mul_f32 v[14:15], v[14:15], v[24:25] op_sel_hi:[1,0]
	s_cmp_lt_i32 s2, s3
	s_waitcnt vmcnt(0)
	v_pk_mul_f32 v[12:13], v[42:43], v[12:13]
	v_pk_mul_f32 v[14:15], v[44:45], v[14:15]
	v_pk_add_f32 v[58:59], v[58:59], 1.0 op_sel_hi:[1,0]
	v_pk_add_f32 v[60:61], v[60:61], 1.0 op_sel_hi:[1,0]
	v_pk_fma_f32 v[12:13], v[58:59], v[12:13], v[74:75]
	v_pk_fma_f32 v[14:15], v[60:61], v[14:15], v[76:77]
	v_pk_mul_f32 v[8:9], v[46:47], v[8:9]
	v_pk_mul_f32 v[10:11], v[48:49], v[10:11]
	v_pk_add_f32 v[62:63], v[62:63], 1.0 op_sel_hi:[1,0]
	v_pk_add_f32 v[64:65], v[64:65], 1.0 op_sel_hi:[1,0]
	v_pk_fma_f32 v[8:9], v[62:63], v[8:9], v[78:79]
	v_pk_fma_f32 v[10:11], v[64:65], v[10:11], v[80:81]
	v_pk_mul_f32 v[4:5], v[50:51], v[4:5]
	v_pk_mul_f32 v[6:7], v[52:53], v[6:7]
	v_pk_add_f32 v[66:67], v[66:67], 1.0 op_sel_hi:[1,0]
	v_pk_add_f32 v[68:69], v[68:69], 1.0 op_sel_hi:[1,0]
	v_pk_fma_f32 v[4:5], v[66:67], v[4:5], v[82:83]
	v_pk_fma_f32 v[6:7], v[68:69], v[6:7], v[84:85]
	v_pk_mul_f32 v[0:1], v[54:55], v[0:1]
	v_pk_mul_f32 v[2:3], v[56:57], v[2:3]
	v_pk_add_f32 v[70:71], v[70:71], 1.0 op_sel_hi:[1,0]
	v_pk_add_f32 v[72:73], v[72:73], 1.0 op_sel_hi:[1,0]
	v_pk_fma_f32 v[0:1], v[70:71], v[0:1], v[86:87]
	v_pk_fma_f32 v[2:3], v[72:73], v[2:3], v[88:89]
	s_nop 0
	v_cvt_pk_bf16_f32 v102, v12, v13
	v_cvt_pk_bf16_f32 v103, v14, v15
	v_cvt_pk_bf16_f32 v104, v8, v9
	v_cvt_pk_bf16_f32 v105, v10, v11
	v_cvt_pk_bf16_f32 v106, v4, v5
	v_cvt_pk_bf16_f32 v107, v6, v7
	v_cvt_pk_bf16_f32 v108, v0, v1
	v_cvt_pk_bf16_f32 v109, v2, v3
	v_lshl_add_u64 v[110:111], v[22:23], 0, s[8:9]
	global_store_dwordx2 v[110:111], v[102:103], off
	global_store_dwordx2 v[110:111], v[104:105], off offset:512
	global_store_dwordx2 v[110:111], v[106:107], off offset:1024
	global_store_dwordx2 v[110:111], v[108:109], off offset:1536
	s_cbranch_scc0 .LBB0_1563
	s_branch .LBB0_1559

; __device__ __forceinline__ float dot4(f32x4 v) { return (v[0] * v[0] + v[1] * v[1]) + (v[2] * v[2] + v[3] * v[3]); }
; __device__ __forceinline__ void norm_row_compute(const float* xp, const float* g, const float* mp, int shoff, int scoff, int lane, u32x2 (&outv)[4], const float* pp = nullptr, float* wb = nullptr) {
;     ...
;     for (int j = 0; j < 4; ++j) { v[j] = *(const f32x4*)(xp + j * 256 + lane * 4);
;         if (pp) { const float* q = pp + j * 256 + lane * 4; v[j] = v[j] + ((*(const f32x4*)q + *(const f32x4*)(q + (size_t)NCTX * D)) + (*(const f32x4*)(q + (size_t)2 * NCTX * D) + *(const f32x4*)(q + (size_t)3 * NCTX * D))); *(f32x4*)(wb + j * 256 + lane * 4) = v[j]; }
;         ss += dot4(v[j]); }
;     ss = wave_sum(ss); const float rstd = rsqrtf(ss * (1.f / 1024.f) + EPS);
.LBB0_1562:
	s_lshl_b64 s[8:9], s[34:35], 12
	v_lshl_add_u64 v[34:35], v[18:19], 0, s[8:9]
	v_add_co_u32_e32 v36, vcc, 0x1000000, v34
	global_load_dwordx4 v[0:3], v25, s[48:49]
	global_load_dwordx4 v[4:7], v[34:35], off
	v_addc_co_u32_e32 v37, vcc, 0, v35, vcc
	global_load_dwordx4 v[8:11], v[36:37], off
	v_add_co_u32_e32 v40, vcc, 0x2000000, v34
	v_lshl_add_u64 v[38:39], v[20:21], 0, s[8:9]
	s_nop 0
	v_addc_co_u32_e32 v41, vcc, 0, v35, vcc
	v_add_co_u32_e32 v42, vcc, 0x3000000, v34
	s_waitcnt vmcnt(0)
	v_pk_add_f32 v[12:13], v[6:7], v[10:11]
	v_addc_co_u32_e32 v43, vcc, 0, v35, vcc
	v_pk_add_f32 v[14:15], v[4:5], v[8:9]
	global_load_dwordx4 v[4:7], v[40:41], off
	global_load_dwordx4 v[8:11], v[42:43], off
	v_cmp_lt_i32_e32 vcc, v226, v220
	s_waitcnt vmcnt(0)
	v_pk_add_f32 v[6:7], v[6:7], v[10:11]
	v_pk_add_f32 v[4:5], v[4:5], v[8:9]
	v_pk_add_f32 v[6:7], v[12:13], v[6:7]
	v_pk_add_f32 v[4:5], v[14:15], v[4:5]
	v_pk_add_f32 v[14:15], v[2:3], v[6:7]
	v_pk_add_f32 v[12:13], v[0:1], v[4:5]
	global_store_dwordx4 v[38:39], v[12:15], off
	global_load_dwordx4 v[0:3], v25, s[48:49] offset:1024
	global_load_dwordx4 v[4:7], v[34:35], off offset:1024
	global_load_dwordx4 v[8:11], v[36:37], off offset:1024
	s_waitcnt vmcnt(0)
	v_pk_add_f32 v[30:31], v[6:7], v[10:11]
	v_pk_add_f32 v[32:33], v[4:5], v[8:9]
	global_load_dwordx4 v[4:7], v[40:41], off offset:1024
	global_load_dwordx4 v[8:11], v[42:43], off offset:1024
	s_waitcnt vmcnt(0)
	v_pk_add_f32 v[6:7], v[6:7], v[10:11]
	v_pk_add_f32 v[4:5], v[4:5], v[8:9]
	v_pk_add_f32 v[6:7], v[30:31], v[6:7]
	v_pk_add_f32 v[4:5], v[32:33], v[4:5]
	v_pk_add_f32 v[10:11], v[2:3], v[6:7]
	v_pk_add_f32 v[8:9], v[0:1], v[4:5]
	global_store_dwordx4 v[38:39], v[8:11], off offset:1024
	global_load_dwordx4 v[0:3], v25, s[48:49] offset:2048
	global_load_dwordx4 v[4:7], v[34:35], off offset:2048
	global_load_dwordx4 v[30:33], v[36:37], off offset:2048
	s_waitcnt vmcnt(0)
	v_pk_add_f32 v[44:45], v[6:7], v[32:33]
	v_pk_add_f32 v[46:47], v[4:5], v[30:31]
	global_load_dwordx4 v[4:7], v[40:41], off offset:2048
	global_load_dwordx4 v[30:33], v[42:43], off offset:2048
	s_waitcnt vmcnt(0)
	v_pk_add_f32 v[6:7], v[6:7], v[32:33]
	v_pk_add_f32 v[4:5], v[4:5], v[30:31]
	v_pk_add_f32 v[6:7], v[44:45], v[6:7]
	v_pk_add_f32 v[4:5], v[46:47], v[4:5]
	v_pk_add_f32 v[6:7], v[2:3], v[6:7]
	v_pk_add_f32 v[4:5], v[0:1], v[4:5]
	global_store_dwordx4 v[38:39], v[4:7], off offset:2048
	global_load_dwordx4 v[0:3], v25, s[48:49] offset:3072
	global_load_dwordx4 v[30:33], v[34:35], off offset:3072
	s_nop 0
	global_load_dwordx4 v[34:37], v[36:37], off offset:3072
	s_waitcnt vmcnt(0)
	v_pk_add_f32 v[44:45], v[32:33], v[36:37]
	v_pk_add_f32 v[46:47], v[30:31], v[34:35]
	global_load_dwordx4 v[30:33], v[40:41], off offset:3072
	global_load_dwordx4 v[34:37], v[42:43], off offset:3072
	s_waitcnt vmcnt(0)
	v_pk_add_f32 v[32:33], v[32:33], v[36:37]
	v_pk_add_f32 v[30:31], v[30:31], v[34:35]
	v_pk_add_f32 v[32:33], v[44:45], v[32:33]
	v_pk_add_f32 v[30:31], v[46:47], v[30:31]
	v_pk_add_f32 v[2:3], v[2:3], v[32:33]
	v_pk_add_f32 v[0:1], v[0:1], v[30:31]
	v_pk_mul_f32 v[30:31], v[14:15], v[14:15]
	v_pk_mul_f32 v[32:33], v[12:13], v[12:13]
	v_mul_f32_e32 v24, v0, v0
	v_pk_mov_b32 v[34:35], v[32:33], v[30:31] op_sel:[1,0]
	v_mov_b32_e32 v33, v31
	v_pk_add_f32 v[30:31], v[34:35], v[32:33]
	v_pk_mul_f32 v[32:33], v[10:11], v[10:11]
	v_pk_mul_f32 v[34:35], v[8:9], v[8:9]
	s_waitcnt lgkmcnt(0)
	v_mul_f32_e32 v29, v1, v1
	v_pk_mov_b32 v[36:37], v[34:35], v[32:33] op_sel:[1,0]
	v_mov_b32_e32 v35, v33
	v_pk_add_f32 v[32:33], v[36:37], v[34:35]
	v_pk_add_f32 v[30:31], v[30:31], v[30:31] op_sel:[0,1] op_sel_hi:[1,0]
	v_pk_add_f32 v[32:33], v[32:33], v[32:33] op_sel:[0,1] op_sel_hi:[1,0]
	v_mov_b32_e32 v31, v24
	v_mov_b32_e32 v33, v29
	v_mul_f32_e32 v24, v5, v5
	v_mul_f32_e32 v34, v2, v2
	v_pk_add_f32 v[30:31], v[30:31], v[32:33]
	v_pk_fma_f32 v[32:33], v[4:5], v[4:5], v[24:25] op_sel_hi:[1,1,0]
	v_mul_f32_e32 v24, v7, v7
	v_mul_f32_e32 v36, v3, v3
	v_mov_b32_e32 v33, v34
	v_pk_fma_f32 v[34:35], v[6:7], v[6:7], v[24:25] op_sel_hi:[1,1,0]
	v_cndmask_b32_e32 v29, v219, v226, vcc
	v_mov_b32_e32 v35, v36
	v_pk_add_f32 v[32:33], v[32:33], v[34:35]
	v_lshlrev_b32_e32 v29, 2, v29
	v_pk_add_f32 v[30:31], v[30:31], v[32:33]
	v_cmp_lt_i32_e32 vcc, v225, v220
	v_add_f32_e32 v24, v30, v31
	global_store_dwordx4 v[38:39], v[0:3], off offset:3072
	s_nop 1
	v_add_f32_dpp v24, v24, v24 quad_perm:[1,0,3,2] row_mask:0xf bank_mask:0xf
	s_nop 1
	v_add_f32_dpp v24, v24, v24 quad_perm:[2,3,0,1] row_mask:0xf bank_mask:0xf
	s_nop 1
	v_add_f32_dpp v24, v24, v24 row_half_mirror row_mask:0xf bank_mask:0xf
	s_nop 1
	v_add_f32_dpp v24, v24, v24 row_mirror row_mask:0xf bank_mask:0xf
	v_mov_b32_e32 v29, v24
	s_nop 1
	v_permlane16_swap_b32_e32 v24, v29
	s_nop 1
	v_add_f32_e32 v24, v24, v29
	v_mov_b32_e32 v29, v24
	s_nop 1
	v_permlane32_swap_b32_e32 v24, v29
	s_nop 1
	v_add_f32_e32 v24, v24, v29
	v_mov_b32_e32 v29, 0
	s_branch .LBB0_1558

; __device__ __forceinline__ float dot4(f32x4 v) { return (v[0] * v[0] + v[1] * v[1]) + (v[2] * v[2] + v[3] * v[3]); }
; __device__ __forceinline__ int fresh_tid() { int t = threadIdx.x; asm volatile("" : "+v"(t)); return t; }
; __global__ void __launch_bounds__(512, 2) fwd_megakernel(Args a) {
;     ...
;     const int ftid = fresh_tid(), lane = ftid & 63, gw = blockIdx.x * NWAVES + __builtin_amdgcn_readfirstlane(ftid >> 6), ngw = G * NWAVES;
;     for (int row_ = gw; row_ < NLAT; row_ += ngw) { const int row = NLAT - 1 - row_;
;         float* xp = out + (size_t)row * D; f32x4 v[4]; float ss = 0.f;
; #pragma unroll
;         for (int j = 0; j < 4; ++j) { v[j] = *(const f32x4*)(xp + j * 256 + lane * 4); ss += dot4(v[j]); }
;         ss = wave_sum(ss); const float rstd = rsqrtf(ss * (1.f / 1024.f) + EPS);
; #pragma unroll
;         for (int j = 0; j < 4; ++j) { const f32x4 gv = *(const f32x4*)(final_g + j * 256 + lane * 4); *(f32x4*)(xp + j * 256 + lane * 4) = v[j] * rstd * gv; }
;     }
.LBB0_1787:
	s_lshl_b64 s[4:5], s[0:1], 12
	v_lshl_add_u64 v[32:33], v[2:3], 0, s[4:5]
	global_load_dwordx4 v[12:15], v[32:33], off
	global_load_dwordx4 v[16:19], v[32:33], off offset:1024
	global_load_dwordx4 v[20:23], v[32:33], off offset:2048
	global_load_dwordx4 v[24:27], v[32:33], off offset:3072
	global_load_dwordx4 v[28:31], v[0:1], off
	s_add_i32 s2, s2, s84
	s_sub_i32 s0, s0, s84
	s_cmp_gt_i32 s2, 0xffff
	s_waitcnt vmcnt(4)
	v_pk_mul_f32 v[34:35], v[14:15], v[14:15]
	v_pk_mul_f32 v[36:37], v[12:13], v[12:13]
	s_waitcnt vmcnt(3)
	v_pk_mul_f32 v[38:39], v[18:19], v[18:19]
	v_pk_mul_f32 v[40:41], v[16:17], v[16:17]
	v_pk_mov_b32 v[46:47], v[36:37], v[34:35] op_sel:[1,0]
	v_mov_b32_e32 v37, v35
	v_pk_mov_b32 v[34:35], v[40:41], v[38:39] op_sel:[1,0]
	v_mov_b32_e32 v41, v39
	s_waitcnt vmcnt(1)
	v_mul_f32_e32 v45, v25, v25
	v_mul_f32_e32 v42, v21, v21
	v_mul_f32_e32 v44, v23, v23
	v_pk_add_f32 v[36:37], v[46:47], v[36:37]
	v_pk_add_f32 v[34:35], v[34:35], v[40:41]
	v_mul_f32_e32 v11, v24, v24
	v_mul_f32_e32 v48, v26, v26
	v_mul_f32_e32 v49, v27, v27
	v_pk_fma_f32 v[38:39], v[20:21], v[20:21], v[42:43] op_sel_hi:[1,1,0]
	v_pk_fma_f32 v[42:43], v[22:23], v[22:23], v[44:45] op_sel_hi:[1,1,0]
	v_pk_add_f32 v[36:37], v[36:37], v[36:37] op_sel:[0,1] op_sel_hi:[1,0]
	v_pk_add_f32 v[34:35], v[34:35], v[34:35] op_sel:[0,1] op_sel_hi:[1,0]
	v_mov_b32_e32 v39, v48
	v_mov_b32_e32 v43, v49
	v_mov_b32_e32 v37, v11
	v_mov_b32_e32 v35, v45
	v_pk_add_f32 v[38:39], v[38:39], v[42:43]
	v_pk_add_f32 v[34:35], v[36:37], v[34:35]
	s_nop 0
	v_pk_add_f32 v[34:35], v[34:35], v[38:39]
	s_nop 0
	v_add_f32_e32 v11, v34, v35
	s_nop 1
	v_add_f32_dpp v11, v11, v11 quad_perm:[1,0,3,2] row_mask:0xf bank_mask:0xf
	s_nop 1
	v_add_f32_dpp v11, v11, v11 quad_perm:[2,3,0,1] row_mask:0xf bank_mask:0xf
	s_nop 1
	v_add_f32_dpp v11, v11, v11 row_half_mirror row_mask:0xf bank_mask:0xf
	s_nop 1
	v_add_f32_dpp v11, v11, v11 row_mirror row_mask:0xf bank_mask:0xf
	v_mov_b32_e32 v34, v11
	s_nop 1
	v_permlane16_swap_b32_e32 v11, v34
	s_nop 1
	v_add_f32_e32 v11, v11, v34
	v_mov_b32_e32 v34, v11
	s_nop 1
	v_permlane32_swap_b32_e32 v11, v34
	s_nop 1
	v_add_f32_e32 v11, v11, v34
	v_fmamk_f32 v11, v11, 0x3a800000, v10
	v_mul_f32_e32 v34, 0x4b800000, v11
	v_cmp_gt_f32_e32 vcc, s3, v11
	s_nop 1
	v_cndmask_b32_e32 v11, v11, v34, vcc
	v_rsq_f32_e32 v11, v11
	s_nop 0
	v_mul_f32_e32 v34, 0x45800000, v11
	v_cndmask_b32_e32 v34, v11, v34, vcc
	v_pk_mul_f32 v[12:13], v[34:35], v[12:13] op_sel_hi:[0,1]
	v_pk_mul_f32 v[14:15], v[34:35], v[14:15] op_sel_hi:[0,1]
	s_waitcnt vmcnt(0)
	v_pk_mul_f32 v[14:15], v[14:15], v[30:31]
	v_pk_mul_f32 v[12:13], v[12:13], v[28:29]
	global_store_dwordx4 v[32:33], v[12:15], off
	global_load_dwordx4 v[12:15], v[0:1], off offset:1024
	v_pk_mul_f32 v[18:19], v[34:35], v[18:19] op_sel_hi:[0,1]
	v_pk_mul_f32 v[16:17], v[34:35], v[16:17] op_sel_hi:[0,1]
	s_waitcnt vmcnt(0)
	v_pk_mul_f32 v[12:13], v[16:17], v[12:13]
	v_pk_mul_f32 v[14:15], v[18:19], v[14:15]
	global_store_dwordx4 v[32:33], v[12:15], off offset:1024
	global_load_dwordx4 v[12:15], v[0:1], off offset:2048
	v_pk_mul_f32 v[16:17], v[34:35], v[22:23] op_sel_hi:[0,1]
	v_pk_mul_f32 v[18:19], v[34:35], v[20:21] op_sel_hi:[0,1]
	s_waitcnt vmcnt(0)
	v_pk_mul_f32 v[12:13], v[18:19], v[12:13]
	v_pk_mul_f32 v[14:15], v[16:17], v[14:15]
	global_store_dwordx4 v[32:33], v[12:15], off offset:2048
	global_load_dwordx4 v[12:15], v[0:1], off offset:3072
	v_pk_mul_f32 v[16:17], v[34:35], v[26:27] op_sel_hi:[0,1]
	v_pk_mul_f32 v[18:19], v[34:35], v[24:25] op_sel_hi:[0,1]
	s_waitcnt vmcnt(0)
	v_pk_mul_f32 v[12:13], v[18:19], v[12:13]
	v_pk_mul_f32 v[14:15], v[16:17], v[14:15]
	global_store_dwordx4 v[32:33], v[12:15], off offset:3072
	s_cbranch_scc0 .LBB0_1787

; __global__ void __launch_bounds__(512, 2) fwd_megakernel(Args a) {
	.amdhsa_kernel _ZN2mk14fwd_megakernelENS_4ArgsE
		.amdhsa_group_segment_fixed_size 0
		.amdhsa_private_segment_fixed_size 0
		.amdhsa_kernarg_size 480
		.amdhsa_user_sgpr_count 2
		.amdhsa_user_sgpr_dispatch_ptr 0
		.amdhsa_user_sgpr_queue_ptr 0
		.amdhsa_user_sgpr_kernarg_segment_ptr 1
		.amdhsa_user_sgpr_dispatch_id 0
		.amdhsa_user_sgpr_kernarg_preload_length 0
		.amdhsa_user_sgpr_kernarg_preload_offset 0
		.amdhsa_user_sgpr_private_segment_size 0
		.amdhsa_uses_dynamic_stack 0
		.amdhsa_enable_private_segment 0
		.amdhsa_system_sgpr_workgroup_id_x 1
		.amdhsa_system_sgpr_workgroup_id_y 0
		.amdhsa_system_sgpr_workgroup_id_z 0
		.amdhsa_system_sgpr_workgroup_info 0
		.amdhsa_system_vgpr_workitem_id 2
		.amdhsa_next_free_vgpr 256
		.amdhsa_next_free_sgpr 102
		.amdhsa_accum_offset 256
		.amdhsa_reserve_vcc 1
		.amdhsa_float_round_mode_32 0
		.amdhsa_float_round_mode_16_64 0
		.amdhsa_float_denorm_mode_32 3
		.amdhsa_float_denorm_mode_16_64 3
		.amdhsa_dx10_clamp 1
		.amdhsa_ieee_mode 1
		.amdhsa_fp16_overflow 0
		.amdhsa_tg_split 0
		.amdhsa_exception_fp_ieee_invalid_op 0
		.amdhsa_exception_fp_denorm_src 0
		.amdhsa_exception_fp_ieee_div_zero 0
		.amdhsa_exception_fp_ieee_overflow 0
		.amdhsa_exception_fp_ieee_underflow 0
		.amdhsa_exception_fp_ieee_inexact 0
		.amdhsa_exception_int_div_zero 0
	.end_amdhsa_kernel

; __global__ void __launch_bounds__(512, 2) fwd_megakernel(Args a) {
amdhsa.kernels:
  - .agpr_count:     0
    .args:
      - .offset:         0
        .size:           224
        .value_kind:     by_value
      - .offset:         224
        .size:           4
        .value_kind:     hidden_block_count_x
      - .offset:         228
        .size:           4
        .value_kind:     hidden_block_count_y
      - .offset:         232
        .size:           4
        .value_kind:     hidden_block_count_z
      - .offset:         236
        .size:           2
        .value_kind:     hidden_group_size_x
      - .offset:         238
        .size:           2
        .value_kind:     hidden_group_size_y
      - .offset:         240
        .size:           2
        .value_kind:     hidden_group_size_z
      - .offset:         242
        .size:           2
        .value_kind:     hidden_remainder_x
      - .offset:         244
        .size:           2
        .value_kind:     hidden_remainder_y
      - .offset:         246
        .size:           2
        .value_kind:     hidden_remainder_z
      - .offset:         264
        .size:           8
        .value_kind:     hidden_global_offset_x
      - .offset:         272
        .size:           8
        .value_kind:     hidden_global_offset_y
      - .offset:         280
        .size:           8
        .value_kind:     hidden_global_offset_z
      - .offset:         288
        .size:           2
        .value_kind:     hidden_grid_dims
      - .offset:         312
        .size:           8
        .value_kind:     hidden_multigrid_sync_arg
      - .offset:         344
        .size:           4
        .value_kind:     hidden_dynamic_lds_size
    .group_segment_fixed_size: 0
    .kernarg_segment_align: 8
    .kernarg_segment_size: 480
    .language:       OpenCL C
    .language_version:
      - 2
      - 0
    .max_flat_workgroup_size: 512
    .name:           _ZN2mk14fwd_megakernelENS_4ArgsE
    .private_segment_fixed_size: 0
    .sgpr_count:     108
    .sgpr_spill_count: 279
    .symbol:         _ZN2mk14fwd_megakernelENS_4ArgsE.kd
    .uniform_work_group_size: 1
    .uses_dynamic_stack: false
    .vgpr_count:     256
    .vgpr_spill_count: 0
    .wavefront_size: 64
